# plus q fragments 1..7 kept in the freed staging VGPRs (loaded once per block) instead of 7 ds_read_b128 per step; K fragment reads issued up front with counted lgkmcnt
# speedup vs baseline: 1.0335x; 1.0040x over previous
; __device__ __forceinline__ void attn2_block(const Block2& B, char* lds) {
;     ...
;     char* qf = lds + A2_Q + pr * 7168 + lane * 16;
;     const bf16x8 q0 = load8<bf16>(B.Q + (size_t)(pr * 32 + r32) * D + hi * 8);
;     if (kh == 0) {
; #pragma unroll
;         for (int d0 = 1; d0 < 8; ++d0) *(bf16x8*)(qf + (d0 - 1) * 1024) = load8<bf16>(B.Q + (size_t)(pr * 32 + r32) * D + d0 * 16 + hi * 8); }
.LBB0_365:
	v_add_f32_e32 v67, v98, v99
	v_add_f32_e32 v92, 0, v67
	v_mul_f32_e32 v93, 0xbe0293ee, v218
	v_fmamk_f32 v65, v65, 0x3e0293ee, v93
	v_exp_f32_e32 v84, v65
	v_fmamk_f32 v65, v79, 0x3e0293ee, v93
	v_exp_f32_e32 v86, v65
	v_fmamk_f32 v65, v73, 0x3e0293ee, v93
	v_exp_f32_e32 v88, v65
	v_fmamk_f32 v65, v69, 0x3e0293ee, v93
	v_exp_f32_e32 v90, v65
	v_fmamk_f32 v65, v68, 0x3e0293ee, v93
	v_exp_f32_e32 v68, v65
	v_fmamk_f32 v65, v75, 0x3e0293ee, v93
	v_fmamk_f32 v67, v71, 0x3e0293ee, v93
	v_exp_f32_e32 v83, v65
	v_fmamk_f32 v65, v72, 0x3e0293ee, v93
	v_exp_f32_e32 v82, v67
	v_fmamk_f32 v67, v70, 0x3e0293ee, v93
	v_exp_f32_e32 v71, v65
	v_fmamk_f32 v65, v78, 0x3e0293ee, v93
	v_exp_f32_e32 v70, v67
	v_exp_f32_e32 v67, v65
	v_fmamk_f32 v65, v74, 0x3e0293ee, v93
	v_exp_f32_e32 v85, v65
	v_fmamk_f32 v65, v81, 0x3e0293ee, v93
	v_fmamk_f32 v66, v66, 0x3e0293ee, v93
	v_exp_f32_e32 v87, v65
	v_fmamk_f32 v65, v80, 0x3e0293ee, v93
	v_exp_f32_e32 v66, v66
	v_exp_f32_e32 v89, v65
	v_fmamk_f32 v65, v77, 0x3e0293ee, v93
	v_fmac_f32_e32 v93, 0x3e0293ee, v76
	v_exp_f32_e32 v91, v65
	v_exp_f32_e32 v69, v93
	v_pk_add_f32 v[72:73], v[82:83], v[70:71]
	v_pk_add_f32 v[74:75], v[66:67], v[84:85]
	v_pk_add_f32 v[76:77], v[90:91], v[68:69]
	v_pk_add_f32 v[72:73], v[72:73], v[74:75]
	v_pk_add_f32 v[74:75], v[86:87], v[88:89]
	s_nop 0
	v_pk_add_f32 v[74:75], v[74:75], v[76:77]
	s_nop 0
	v_pk_add_f32 v[72:73], v[72:73], v[74:75]
	s_nop 0
	v_pk_add_f32 v[72:73], v[72:73], v[72:73] op_sel:[0,1] op_sel_hi:[1,0]
	s_nop 0
	v_mov_b32_e32 v65, v72
	s_nop 1
	v_permlane32_swap_b32_e32 v72, v65
	v_add_f32_e32 v227, v72, v65
	v_fmac_f32_e32 v227, v92, v97
	v_cvt_pk_bf16_f32 v172, v82, v70
	v_cvt_pk_bf16_f32 v173, v66, v84
	v_cvt_pk_bf16_f32 v174, v86, v88
	v_cvt_pk_bf16_f32 v175, v90, v68
	v_cvt_pk_bf16_f32 v176, v83, v71
	v_cvt_pk_bf16_f32 v177, v67, v85
	v_cvt_pk_bf16_f32 v178, v87, v89
	v_cvt_pk_bf16_f32 v179, v91, v69
	s_nop 0
	v_permlane32_swap_b32_e32 v172, v174
	v_permlane32_swap_b32_e32 v173, v175
	v_permlane32_swap_b32_e32 v176, v178
	v_permlane32_swap_b32_e32 v177, v179
	ds_write_b128 v219, v[172:175] offset:16384
	ds_write_b128 v219, v[176:179] offset:17408
	s_waitcnt lgkmcnt(0)
	s_barrier
	s_and_b64 vcc, exec, s[4:5]
	s_cbranch_vccnz .LBB0_404
	s_add_i32 s53, s84, -2
	s_mov_b32 s87, 5
	s_waitcnt vmcnt(0)
	ds_read_b128 v[148:151], v210
	ds_read_b128 v[152:155], v210 offset:1024
	ds_read_b128 v[156:159], v210 offset:2048
	ds_read_b128 v[160:163], v210 offset:3072
	ds_read_b128 v[164:167], v210 offset:4096
	ds_read_b128 v[168:171], v210 offset:5120
	ds_read_b128 v[252:255], v210 offset:6144
	s_waitcnt lgkmcnt(0)
	s_branch .LBB0_368

; template <int KB> __device__ __forceinline__ void qkt_half(f32x16& p, const char* K_lds, int r32, int hi, int kh, const char* qf, bf16x8 q0) {
;     p = f32x16{};
;     const char* kb[4];
; #pragma unroll
;     for (int dd = 0; dd < 4; ++dd) kb[dd] = K_lds + KB * SHM_K + kh * 8192 + KSWZ(r32, (dd * 16 + hi * 8) * 2);
; #pragma unroll
;     for (int d0 = 0; d0 < 8; ++d0) { const bf16x8 b0 = *reinterpret_cast<const bf16x8*>(kb[d0 & 3] + (d0 >> 2) * 128); const bf16x8 q = d0 == 0 ? q0 : *reinterpret_cast<const bf16x8*>(qf + (d0 - 1) * 1024); p = __builtin_amdgcn_mfma_f32_32x32x16_bf16(b0, q, p, 0, 0, 0); }
; }
.LBB0_369:
	ds_read_b128 v[184:187], v220 offset:16384
	ds_read_b128 v[180:183], v220 offset:17408
	ds_read_b128 v[64:67], v211
	ds_read_b128 v[68:71], v212
	ds_read_b128 v[72:75], v213
	ds_read_b128 v[76:79], v214
	ds_read_b128 v[80:83], v211 offset:128
	ds_read_b128 v[84:87], v212 offset:128
	ds_read_b128 v[88:91], v213 offset:128
	ds_read_b128 v[92:95], v214 offset:128
	s_waitcnt lgkmcnt(7)
	v_mfma_f32_32x32x16_bf16 v[128:143], v[64:67], v[144:147], 0
	s_waitcnt lgkmcnt(6)
	v_mfma_f32_32x32x16_bf16 v[128:143], v[68:71], v[148:151], v[128:143]
	s_waitcnt lgkmcnt(5)
	v_mfma_f32_32x32x16_bf16 v[128:143], v[72:75], v[152:155], v[128:143]
	s_waitcnt lgkmcnt(4)
	v_mfma_f32_32x32x16_bf16 v[128:143], v[76:79], v[156:159], v[128:143]
	s_waitcnt lgkmcnt(3)
	v_mfma_f32_32x32x16_bf16 v[128:143], v[80:83], v[160:163], v[128:143]
	s_waitcnt lgkmcnt(2)
	v_mfma_f32_32x32x16_bf16 v[128:143], v[84:87], v[164:167], v[128:143]
	s_waitcnt lgkmcnt(1)
	v_mfma_f32_32x32x16_bf16 v[128:143], v[88:91], v[168:171], v[128:143]
	s_waitcnt lgkmcnt(0)
	v_mfma_f32_32x32x16_bf16 v[128:143], v[92:95], v[252:255], v[128:143]
	s_mov_b64 s[4:5], -1
	s_and_b64 vcc, exec, s[48:49]
	s_cbranch_vccz .LBB0_371
	ds_read_b64_tr_b16 v[80:81], v194 offset:0xc000
	ds_read_b64_tr_b16 v[82:83], v194 offset:0xc800
	ds_read_b64_tr_b16 v[84:85], v194 offset:0xd000
	ds_read_b64_tr_b16 v[86:87], v194 offset:0xd800
	ds_read_b64_tr_b16 v[88:89], v194 offset:0xe000
	ds_read_b64_tr_b16 v[90:91], v194 offset:0xe800
	ds_read_b64_tr_b16 v[92:93], v194 offset:0xf000
	ds_read_b64_tr_b16 v[94:95], v194 offset:0xf800
	s_waitcnt lgkmcnt(0)
	s_nop 0
	v_mfma_f32_32x32x16_bf16 v[64:79], v[184:187], v[80:83], v[0:15]
	ds_read_b64_tr_b16 v[96:97], v194 offset:0xc200
	ds_read_b64_tr_b16 v[98:99], v194 offset:0xca00
	ds_read_b64_tr_b16 v[100:101], v194 offset:0xd200
	ds_read_b64_tr_b16 v[102:103], v194 offset:0xda00
	ds_read_b64_tr_b16 v[104:105], v194 offset:0xe200
	ds_read_b64_tr_b16 v[106:107], v194 offset:0xea00
	ds_read_b64_tr_b16 v[108:109], v194 offset:0xf200
	v_mfma_f32_32x32x16_bf16 v[64:79], v[180:183], v[84:87], v[64:79]
	ds_read_b64_tr_b16 v[110:111], v194 offset:0xfa00
	v_mfma_f32_32x32x16_bf16 v[64:79], v[172:175], v[88:91], v[64:79]
	v_mfma_f32_32x32x16_bf16 v[64:79], v[176:179], v[92:95], v[64:79]
	s_waitcnt lgkmcnt(0)
	v_mfma_f32_32x32x16_bf16 v[80:95], v[184:187], v[96:99], v[16:31]
	ds_read_b64_tr_b16 v[112:113], v194 offset:0xc400
	ds_read_b64_tr_b16 v[114:115], v194 offset:0xcc00
	ds_read_b64_tr_b16 v[116:117], v194 offset:0xd400
	ds_read_b64_tr_b16 v[118:119], v194 offset:0xdc00
	ds_read_b64_tr_b16 v[120:121], v194 offset:0xe400
	ds_read_b64_tr_b16 v[122:123], v194 offset:0xec00
	ds_read_b64_tr_b16 v[124:125], v194 offset:0xf400
	v_mfma_f32_32x32x16_bf16 v[80:95], v[180:183], v[100:103], v[80:95]
	ds_read_b64_tr_b16 v[126:127], v194 offset:0xfc00
	s_add_i32 s38, s87, -3
	s_add_i32 s50, s53, 1
	s_and_b64 s[4:5], s[46:47], exec
	s_cselect_b32 s4, s38, s50
	s_lshl_b32 s4, s4, 6
	s_cmp_le_i32 s4, s86
	s_cbranch_scc0 .Lm0_h1B_mk

; template <int KB> __device__ __forceinline__ void qkt_half(f32x16& p, const char* K_lds, int r32, int hi, int kh, const char* qf, bf16x8 q0) {
;     p = f32x16{};
;     const char* kb[4];
; #pragma unroll
;     for (int dd = 0; dd < 4; ++dd) kb[dd] = K_lds + KB * SHM_K + kh * 8192 + KSWZ(r32, (dd * 16 + hi * 8) * 2);
; #pragma unroll
;     for (int d0 = 0; d0 < 8; ++d0) { const bf16x8 b0 = *reinterpret_cast<const bf16x8*>(kb[d0 & 3] + (d0 >> 2) * 128); const bf16x8 q = d0 == 0 ? q0 : *reinterpret_cast<const bf16x8*>(qf + (d0 - 1) * 1024); p = __builtin_amdgcn_mfma_f32_32x32x16_bf16(b0, q, p, 0, 0, 0); }
; }
.LBB0_386:
	ds_read_b128 v[184:187], v220
	ds_read_b128 v[180:183], v220 offset:1024
	ds_read_b128 v[0:3], v222
	ds_read_b128 v[4:7], v223
	ds_read_b128 v[8:11], v224
	ds_read_b128 v[12:15], v225
	ds_read_b128 v[16:19], v222 offset:128
	ds_read_b128 v[20:23], v223 offset:128
	ds_read_b128 v[24:27], v224 offset:128
	ds_read_b128 v[28:31], v225 offset:128
	s_waitcnt lgkmcnt(7)
	v_mfma_f32_32x32x16_bf16 v[128:143], v[0:3], v[144:147], 0
	s_waitcnt lgkmcnt(6)
	v_mfma_f32_32x32x16_bf16 v[128:143], v[4:7], v[148:151], v[128:143]
	s_waitcnt lgkmcnt(5)
	v_mfma_f32_32x32x16_bf16 v[128:143], v[8:11], v[152:155], v[128:143]
	s_waitcnt lgkmcnt(4)
	v_mfma_f32_32x32x16_bf16 v[128:143], v[12:15], v[156:159], v[128:143]
	s_waitcnt lgkmcnt(3)
	v_mfma_f32_32x32x16_bf16 v[128:143], v[16:19], v[160:163], v[128:143]
	s_waitcnt lgkmcnt(2)
	v_mfma_f32_32x32x16_bf16 v[128:143], v[20:23], v[164:167], v[128:143]
	s_waitcnt lgkmcnt(1)
	v_mfma_f32_32x32x16_bf16 v[128:143], v[24:27], v[168:171], v[128:143]
	s_waitcnt lgkmcnt(0)
	v_mfma_f32_32x32x16_bf16 v[128:143], v[28:31], v[252:255], v[128:143]
	s_mov_b64 s[4:5], -1
	s_and_b64 vcc, exec, s[48:49]
	s_cbranch_vccz .LBB0_388
	ds_read_b64_tr_b16 v[16:17], v194 offset:0x4000
	ds_read_b64_tr_b16 v[18:19], v194 offset:0x4800
	ds_read_b64_tr_b16 v[20:21], v194 offset:0x5000
	ds_read_b64_tr_b16 v[22:23], v194 offset:0x5800
	ds_read_b64_tr_b16 v[24:25], v194 offset:0x6000
	ds_read_b64_tr_b16 v[26:27], v194 offset:0x6800
	ds_read_b64_tr_b16 v[28:29], v194 offset:0x7000
	ds_read_b64_tr_b16 v[30:31], v194 offset:0x7800
	s_waitcnt lgkmcnt(0)
	s_nop 0
	v_mfma_f32_32x32x16_bf16 v[0:15], v[184:187], v[16:19], v[64:79]
	ds_read_b64_tr_b16 v[32:33], v194 offset:0x4200
	ds_read_b64_tr_b16 v[34:35], v194 offset:0x4a00
	ds_read_b64_tr_b16 v[36:37], v194 offset:0x5200
	ds_read_b64_tr_b16 v[38:39], v194 offset:0x5a00
	ds_read_b64_tr_b16 v[40:41], v194 offset:0x6200
	ds_read_b64_tr_b16 v[42:43], v194 offset:0x6a00
	ds_read_b64_tr_b16 v[44:45], v194 offset:0x7200
	v_mfma_f32_32x32x16_bf16 v[0:15], v[180:183], v[20:23], v[0:15]
	ds_read_b64_tr_b16 v[46:47], v194 offset:0x7a00
	v_mfma_f32_32x32x16_bf16 v[0:15], v[172:175], v[24:27], v[0:15]
	v_mfma_f32_32x32x16_bf16 v[0:15], v[176:179], v[28:31], v[0:15]
	s_waitcnt lgkmcnt(0)
	v_mfma_f32_32x32x16_bf16 v[16:31], v[184:187], v[32:35], v[80:95]
	ds_read_b64_tr_b16 v[48:49], v194 offset:0x4400
	ds_read_b64_tr_b16 v[50:51], v194 offset:0x4c00
	ds_read_b64_tr_b16 v[52:53], v194 offset:0x5400
	ds_read_b64_tr_b16 v[54:55], v194 offset:0x5c00
	ds_read_b64_tr_b16 v[56:57], v194 offset:0x6400
	ds_read_b64_tr_b16 v[58:59], v194 offset:0x6c00
	ds_read_b64_tr_b16 v[60:61], v194 offset:0x7400
	v_mfma_f32_32x32x16_bf16 v[16:31], v[180:183], v[36:39], v[16:31]
	ds_read_b64_tr_b16 v[62:63], v194 offset:0x7c00
	s_and_b64 s[4:5], s[46:47], exec
	s_cselect_b32 s4, s89, s53
	s_lshl_b32 s4, s4, 6
	s_cmp_le_i32 s4, s86
	s_cbranch_scc0 .Lm0_h2B_mk
